# diff loop: K tile DMA issued two tiles ahead after the mid barrier, V one ahead; no vmcnt at iteration end
# baseline (speedup 1.0000x reference)
; DI void diff_pass(const bf16_t* __restrict__ qrow  , const bf16_t* __restrict__ kg, const bf16_t* __restrict__ vg,
;                   int nkt, int q0, float negM2, f32x16 (&O)[4], float& lsum, char* lds) {
;     ...
;     bf16x8 qf[4];
; #pragma unroll
;     for (int ks = 0; ks < 4; ++ks) qf[ks] = *(const bf16x8*)(qrow + 16 * ks + 8 * h);
; #pragma unroll
;     for (int d = 0; d < 4; ++d) O[d] = zero16();
;     lsum = 0.f;
;     const f32x16 minit = splat16(negM2);
;     __syncthreads();
;     __builtin_amdgcn_global_load_lds((const unsigned*)kgs, (lds_ptr_t)(lds + wb), 16, 0, 0);
;     __builtin_amdgcn_global_load_lds((const unsigned*)vgs, (lds_ptr_t)(lds + 8192 + wb), 16, 0, 0);
;     __builtin_amdgcn_global_load_lds((const unsigned*)(vgs + (size_t)64 * kS), (lds_ptr_t)(lds + 16384 + wb), 16, 0, 0);
;     asm volatile("s_waitcnt vmcnt(0)" ::: "memory");
;     __syncthreads();
;     for (int kt = 0; kt < nkt; ++kt) {
;         char* st = lds + (kt & 1) * 24576;
;         if (kt + 1 < nkt) {
;             char* st2 = lds + ((kt + 1) & 1) * 24576 + wb;
;             __builtin_amdgcn_global_load_lds((const unsigned*)(kgs + (size_t)(kt + 1) * 64 * 512), (lds_ptr_t)(st2), 16, 0, 0);
;             __builtin_amdgcn_global_load_lds((const unsigned*)(vgs + (kt + 1) * 64), (lds_ptr_t)(st2 + 8192), 16, 0, 0);
;             __builtin_amdgcn_global_load_lds((const unsigned*)(vgs + (size_t)64 * kS + (kt + 1) * 64), (lds_ptr_t)(st2 + 16384), 16, 0, 0);
;         }
;     ...
;             bf16x8 pf[4];
;             pf[0] = pack8(Sx[0], 0); pf[1] = pack8(Sx[0], 1); pf[2] = pack8(Sx[1], 0); pf[3] = pack8(Sx[1], 1);
;             {
;                 bf16x8 vf[2][4];
; #pragma unroll
;                 for (int db = 0; db < 4; ++db) vf[0][db] = *(const bf16x8*)(st + 8192 + (32 * db + l31) * 128 + ((h ^ f) << 4));
; #pragma unroll
;                 for (int s = 0; s < 4; ++s) {
;                     if (s < 3) {
; #pragma unroll
;                         for (int db = 0; db < 4; ++db) vf[(s + 1) & 1][db] = *(const bf16x8*)(st + 8192 + (32 * db + l31) * 128 + (((2 * (s + 1) + h) ^ f) << 4));
;                     }
; #pragma unroll
;                     for (int db = 0; db < 4; ++db) O[db] = MFMA(vf[s & 1][db], pf[s], O[db]);
;                     __builtin_amdgcn_sched_barrier(0);
;                 }
;             }
.LBB0_85:
	v_mov_b32_e32 v8, v162
	s_lshl_b64 s[28:29], s[28:29], 1
	v_lshrrev_b32_e32 v6, 4, v8
	v_and_b32_e32 v0, 7, v8
	v_bitop3_b32 v6, v6, 7, v8 bitop3:0x48
	v_sub_u32_e32 v0, v6, v0
	v_bfe_u32 v9, v8, 5, 1
	v_lshlrev_b32_e32 v6, 3, v0
	v_lshlrev_b32_e32 v0, 4, v8
	v_lshl_add_u64 v[4:5], v[144:145], 0, s[28:29]
	v_ashrrev_i32_e32 v7, 31, v6
	v_and_b32_e32 v187, 0xfffffc00, v0
	v_lshlrev_b32_e32 v0, 4, v9
	v_lshl_add_u64 v[2:3], v[152:153], 0, s[28:29]
	v_lshlrev_b64 v[158:159], 1, v[6:7]
	v_lshl_add_u64 v[4:5], v[4:5], 0, v[0:1]
	v_readfirstlane_b32 s30, v187
	v_add_u32_e32 v0, 0x2000, v187
	v_lshl_add_u64 v[2:3], v[2:3], 0, v[158:159]
	global_load_dwordx4 v[140:143], v[4:5], off
	global_load_dwordx4 v[136:139], v[4:5], off offset:32
	global_load_dwordx4 v[132:135], v[4:5], off offset:64
	global_load_dwordx4 v[128:131], v[4:5], off offset:96
	s_mov_b32 m0, s30
	v_readfirstlane_b32 s30, v0
	v_add_u32_e32 v0, 0x4000, v187
	v_lshl_add_u64 v[4:5], v[150:151], 0, v[158:159]
	s_barrier
	global_load_lds_dwordx4 v[2:3], off
	v_add_u32_e32 v218, 0x6000, v187
	s_mov_b64 s[0:1], 0x10000
	v_lshl_add_u64 v[216:217], v[2:3], 0, s[0:1]
	v_readfirstlane_b32 s32, v218
	s_mov_b32 m0, s32
	s_nop 0
	global_load_lds_dwordx4 v[216:217], off
	s_mov_b32 m0, s30
	v_readfirstlane_b32 s30, v0
	global_load_lds_dwordx4 v[4:5], off
	v_lshl_add_u64 v[2:3], v[4:5], 0, s[94:95]
	s_mov_b32 m0, s30
	v_lshrrev_b32_e32 v0, 5, v8
	global_load_lds_dwordx4 v[2:3], off
	v_bfe_u32 v3, v8, 1, 3
	v_bitop3_b32 v0, v0, v3, 1 bitop3:0x6c
	v_lshlrev_b32_e32 v189, 4, v0
	v_bitop3_b32 v0, v9, v3, 2 bitop3:0x36
	v_lshlrev_b32_e32 v190, 4, v0
	v_bitop3_b32 v0, v9, v3, 4 bitop3:0x36
	v_and_b32_e32 v2, 31, v8
	s_waitcnt vmcnt(0)
	v_lshlrev_b32_e32 v191, 4, v0
	v_bitop3_b32 v0, v9, v3, 6 bitop3:0x36
	v_mov_b32_e32 v14, v1
	v_mov_b32_e32 v15, v1
	v_or_b32_e32 v184, v2, v148
	v_lshlrev_b32_e32 v188, 7, v2
	v_lshlrev_b32_e32 v185, 2, v9
	v_lshlrev_b32_e32 v192, 4, v0
	v_mov_b32_e32 v0, v1
	v_mov_b32_e32 v2, v1
	v_mov_b32_e32 v3, v1
	v_mov_b32_e32 v4, v1
	v_mov_b32_e32 v5, v1
	v_mov_b32_e32 v6, v1
	v_mov_b32_e32 v7, v1
	v_mov_b32_e32 v8, v1
	v_mov_b32_e32 v9, v1
	v_mov_b32_e32 v10, v1
	v_mov_b32_e32 v11, v1
	v_mov_b32_e32 v12, v1
	v_mov_b32_e32 v13, v1
	v_mov_b64_e32 v[46:47], v[14:15]
	v_mov_b64_e32 v[62:63], v[14:15]
	v_mov_b64_e32 v[78:79], v[14:15]
	v_mov_b64_e32 v[94:95], v[14:15]
	s_mov_b32 s54, 1
	v_lshl_add_u64 v[160:161], v[156:157], 0, s[28:29]
	s_mov_b32 s55, 0
	v_mov_b32_e32 v186, 0
	v_mov_b64_e32 v[164:165], v[154:155]
	v_mov_b64_e32 v[44:45], v[12:13]
	v_mov_b64_e32 v[42:43], v[10:11]
	v_mov_b64_e32 v[40:41], v[8:9]
	v_mov_b64_e32 v[38:39], v[6:7]
	v_mov_b64_e32 v[36:37], v[4:5]
	v_mov_b64_e32 v[34:35], v[2:3]
	v_mov_b64_e32 v[32:33], v[0:1]
	v_mov_b64_e32 v[60:61], v[12:13]
	v_mov_b64_e32 v[58:59], v[10:11]
	v_mov_b64_e32 v[56:57], v[8:9]
	v_mov_b64_e32 v[54:55], v[6:7]
	v_mov_b64_e32 v[52:53], v[4:5]
	v_mov_b64_e32 v[50:51], v[2:3]
	v_mov_b64_e32 v[48:49], v[0:1]
	v_mov_b64_e32 v[76:77], v[12:13]
	v_mov_b64_e32 v[74:75], v[10:11]
	v_mov_b64_e32 v[72:73], v[8:9]
	v_mov_b64_e32 v[70:71], v[6:7]
	v_mov_b64_e32 v[68:69], v[4:5]
	v_mov_b64_e32 v[66:67], v[2:3]
	v_mov_b64_e32 v[64:65], v[0:1]
	v_mov_b64_e32 v[92:93], v[12:13]
	v_mov_b64_e32 v[90:91], v[10:11]
	v_mov_b64_e32 v[88:89], v[8:9]
	v_mov_b64_e32 v[86:87], v[6:7]
	v_mov_b64_e32 v[84:85], v[4:5]
	v_mov_b64_e32 v[82:83], v[2:3]
	v_mov_b64_e32 v[80:81], v[0:1]
	s_waitcnt vmcnt(0) lgkmcnt(0)
	s_barrier
	s_branch .LBB0_88
.LBB0_86:
	s_or_b64 exec, exec, s[30:31]
	s_waitcnt vmcnt(2)
	s_barrier
	s_and_b32 s0, 1, s54
	s_cselect_b32 s0, 0, 0x6000
	v_add_u32_e32 v218, s0, v187
	v_lshl_add_u64 v[216:217], v[160:161], 0, v[158:159]
	s_mov_b64 s[0:1], 0x10000
	v_readfirstlane_b32 s32, v218
	v_lshl_add_u64 v[216:217], v[216:217], 0, s[0:1]
	s_mov_b32 m0, s32
	s_nop 0
	global_load_lds_dwordx4 v[216:217], off
	ds_read_b128 v[114:117], v195 offset:8192
	ds_read_b128 v[122:125], v195 offset:12288
	v_cvt_pk_bf16_f32 v118, v2, v4
	v_cvt_pk_bf16_f32 v120, v10, v12
	ds_read_b128 v[196:199], v195 offset:16384
	v_cvt_pk_bf16_f32 v4, v11, v13
	ds_read_b128 v[10:13], v195 offset:20480
	v_cvt_pk_bf16_f32 v119, v6, v8
	v_cvt_pk_bf16_f32 v121, v14, v96
	v_cvt_pk_bf16_f32 v2, v3, v5
	v_cvt_pk_bf16_f32 v3, v7, v9
	s_waitcnt lgkmcnt(0)
	v_mfma_f32_32x32x16_bf16 v[80:95], v[114:117], v[118:121], v[80:95]
	v_cvt_pk_bf16_f32 v114, v100, v104
	v_cvt_pk_bf16_f32 v115, v98, v102
	v_cvt_pk_bf16_f32 v116, v106, v108
	v_cvt_pk_bf16_f32 v117, v112, v110
	v_cvt_pk_bf16_f32 v5, v15, v97
	v_cvt_pk_bf16_f32 v6, v101, v105
	v_cvt_pk_bf16_f32 v7, v99, v103
	v_mfma_f32_32x32x16_bf16 v[64:79], v[122:125], v[118:121], v[64:79]
	v_cvt_pk_bf16_f32 v8, v107, v109
	v_cvt_pk_bf16_f32 v9, v113, v111
	ds_read_b128 v[96:99], v194 offset:8192
	ds_read_b128 v[100:103], v194 offset:12288
	ds_read_b128 v[104:107], v194 offset:16384
	ds_read_b128 v[108:111], v194 offset:20480
	v_mfma_f32_32x32x16_bf16 v[48:63], v[196:199], v[118:121], v[48:63]
	v_mfma_f32_32x32x16_bf16 v[32:47], v[10:13], v[118:121], v[32:47]
	s_waitcnt lgkmcnt(0)
	v_mfma_f32_32x32x16_bf16 v[80:95], v[96:99], v[114:117], v[80:95]
	v_mfma_f32_32x32x16_bf16 v[64:79], v[100:103], v[114:117], v[64:79]
	v_mfma_f32_32x32x16_bf16 v[48:63], v[104:107], v[114:117], v[48:63]
	ds_read_b128 v[10:13], v193 offset:8192
	ds_read_b128 v[96:99], v193 offset:12288
	ds_read_b128 v[100:103], v193 offset:16384
	ds_read_b128 v[104:107], v193 offset:20480
	v_mfma_f32_32x32x16_bf16 v[32:47], v[108:111], v[114:117], v[32:47]
	s_waitcnt lgkmcnt(0)
	v_mfma_f32_32x32x16_bf16 v[80:95], v[10:13], v[2:5], v[80:95]
	v_mfma_f32_32x32x16_bf16 v[64:79], v[96:99], v[2:5], v[64:79]
	v_mfma_f32_32x32x16_bf16 v[48:63], v[100:103], v[2:5], v[48:63]
	ds_read_b128 v[10:13], v0 offset:8192
	ds_read_b128 v[96:99], v0 offset:12288
	ds_read_b128 v[100:103], v0 offset:16384
	ds_read_b128 v[108:111], v0 offset:20480
	v_mfma_f32_32x32x16_bf16 v[32:47], v[104:107], v[2:5], v[32:47]
	s_waitcnt lgkmcnt(0)
	v_mfma_f32_32x32x16_bf16 v[80:95], v[10:13], v[6:9], v[80:95]
	v_mfma_f32_32x32x16_bf16 v[64:79], v[96:99], v[6:9], v[64:79]
	v_mfma_f32_32x32x16_bf16 v[48:63], v[100:103], v[6:9], v[48:63]
	v_mfma_f32_32x32x16_bf16 v[32:47], v[108:111], v[6:9], v[32:47]
; #define MFMA(a, b, c) __builtin_amdgcn_mfma_f32_32x32x16_bf16((a), (b), (c), 0, 0, 0)
; DI float fexp2(float x) { return __builtin_amdgcn_exp2f(x); }
; DI void diff_pass(const bf16_t* __restrict__ qrow  , const bf16_t* __restrict__ kg, const bf16_t* __restrict__ vg,
;                   int nkt, int q0, float negM2, f32x16 (&O)[4], float& lsum, char* lds) {
;     ...
;     for (int kt = 0; kt < nkt; ++kt) {
;         char* st = lds + (kt & 1) * 24576;
;         if (kt + 1 < nkt) {
;             char* st2 = lds + ((kt + 1) & 1) * 24576 + wb;
;             __builtin_amdgcn_global_load_lds((const unsigned*)(kgs + (size_t)(kt + 1) * 64 * 512), (lds_ptr_t)(st2), 16, 0, 0);
;             __builtin_amdgcn_global_load_lds((const unsigned*)(vgs + (kt + 1) * 64), (lds_ptr_t)(st2 + 8192), 16, 0, 0);
;             __builtin_amdgcn_global_load_lds((const unsigned*)(vgs + (size_t)64 * kS + (kt + 1) * 64), (lds_ptr_t)(st2 + 16384), 16, 0, 0);
;         }
;         __builtin_amdgcn_sched_barrier(0);
;         if (kt * 64 <= q0 + 31) {
;             f32x16 Sx[2];
;             {
;                 bf16x8 kf[2][4];
; #pragma unroll
;                 for (int kb = 0; kb < 2; ++kb)
; #pragma unroll
;                     for (int ks = 0; ks < 4; ++ks) kf[kb][ks] = *(const bf16x8*)(st + (32 * kb + l31) * 128 + (((2 * ks + h) ^ f) << 4));
;                 __builtin_amdgcn_sched_barrier(0);
; #pragma unroll
;                 for (int ks = 0; ks < 4; ++ks)
; #pragma unroll
;                     for (int kb = 0; kb < 2; ++kb) Sx[kb] = ks == 0 ? MFMA(kf[kb][0], qf[0], minit) : MFMA(kf[kb][ks], qf[ks], Sx[kb]);
;             }
;             if (kt * 64 + 63 > q0) {
; #pragma unroll
;                 for (int kb = 0; kb < 2; ++kb)
; #pragma unroll
;                     for (int i = 0; i < 16; ++i) {
;                         float p = fexp2(Sx[kb][i]);
;                         const int key = kt * 64 + 32 * kb + (i & 3) + 8 * (i >> 2) + 4 * h;
;                         if (key > qpos) p = 0.f;
;                         lsum += p; Sx[kb][i] = p;
;                     }
.LBB0_87:
	s_or_b64 exec, exec, s[28:29]
	s_nop 0
	s_add_i32 s55, s55, 64
	s_add_i32 s54, s54, 1
	s_mov_b64 s[28:29], 0x10000
	v_lshl_add_u64 v[164:165], v[164:165], 0, s[18:19]
	s_cmp_eq_u32 s35, s55
	v_lshl_add_u64 v[160:161], v[160:161], 0, s[28:29]
	s_waitcnt lgkmcnt(0)
	s_barrier
	s_cbranch_scc1 .LBB0_93
.LBB0_88:
	s_and_b32 s30, 1, s54
	s_cselect_b32 s28, 0x6000, 0
	v_add_u32_e32 v0, s28, v187
	v_lshl_add_u64 v[2:3], v[160:161], 0, v[158:159]
	v_readfirstlane_b32 s28, v0
	s_mov_b32 m0, s28
	s_mov_b64 s[28:29], 0x1b800080
	s_nop 0
	v_lshl_add_u64 v[2:3], v[164:165], 0, v[158:159]
	v_add_u32_e32 v6, 0x2000, v0
	v_lshl_add_u64 v[4:5], v[2:3], 0, s[28:29]
	v_readfirstlane_b32 s28, v6
	s_mov_b32 m0, s28
	s_mov_b64 s[28:29], 0x1b900080
	v_add_u32_e32 v0, 0x4000, v0
	v_lshl_add_u64 v[2:3], v[2:3], 0, s[28:29]
	v_readfirstlane_b32 s28, v0
	global_load_lds_dwordx4 v[4:5], off
	s_mov_b32 m0, s28
	s_nop 0
	global_load_lds_dwordx4 v[2:3], off
	v_cmp_le_i32_e32 vcc, s55, v171
	s_and_saveexec_b64 s[28:29], vcc
	s_cbranch_execz .Ldf_skipmid
	s_cmp_eq_u32 s30, 1
	s_cselect_b32 s30, 0, 0x6000
	v_or_b32_e32 v0, s30, v188
	v_add_u32_e32 v195, v0, v189
	v_add_u32_e32 v194, v0, v190
	v_add_u32_e32 v193, v0, v191
	v_add_u32_e32 v0, v0, v192
	s_add_i32 s30, s55, 63
	v_cmp_le_i32_e32 vcc, s30, v148
	s_cbranch_vccnz .Ldf_fast
	ds_read_b128 v[2:5], v195
	ds_read_b128 v[6:9], v195 offset:4096
	ds_read_b128 v[10:13], v194
	ds_read_b128 v[196:199], v194 offset:4096
	ds_read_b128 v[200:203], v193
	ds_read_b128 v[204:207], v193 offset:4096
	ds_read_b128 v[208:211], v0
	ds_read_b128 v[212:215], v0 offset:4096
	s_waitcnt lgkmcnt(0)
	v_mfma_f32_32x32x16_bf16 v[96:111], v[2:5], v[140:143], v[16:31]
	s_add_i32 s30, s55, 63
	v_cmp_le_i32_e32 vcc, s30, v148
	v_mfma_f32_32x32x16_bf16 v[112:127], v[6:9], v[140:143], v[16:31]
	v_mfma_f32_32x32x16_bf16 v[96:111], v[10:13], v[136:139], v[96:111]
	v_mfma_f32_32x32x16_bf16 v[112:127], v[196:199], v[136:139], v[112:127]
	v_mfma_f32_32x32x16_bf16 v[96:111], v[200:203], v[132:135], v[96:111]
	v_mfma_f32_32x32x16_bf16 v[112:127], v[204:207], v[132:135], v[112:127]
	v_mfma_f32_32x32x16_bf16 v[96:111], v[208:211], v[128:131], v[96:111]
	v_mfma_f32_32x32x16_bf16 v[112:127], v[212:215], v[128:131], v[112:127]
	s_nop 10
	v_exp_f32_e32 v2, v96
	v_exp_f32_e32 v4, v97
	v_exp_f32_e32 v6, v98
	v_exp_f32_e32 v8, v99
	v_exp_f32_e32 v10, v100
	v_exp_f32_e32 v12, v101
	v_exp_f32_e32 v14, v102
	v_exp_f32_e32 v3, v112
	v_exp_f32_e32 v5, v113
	v_exp_f32_e32 v7, v114
	v_exp_f32_e32 v9, v115
	v_exp_f32_e32 v11, v116
	v_exp_f32_e32 v13, v117
	v_exp_f32_e32 v15, v118
	v_exp_f32_e32 v96, v103
	v_exp_f32_e32 v97, v119
	v_exp_f32_e32 v100, v104
	v_exp_f32_e32 v101, v120
	v_exp_f32_e32 v104, v105
	v_exp_f32_e32 v105, v121
	v_exp_f32_e32 v98, v106
	v_exp_f32_e32 v99, v122
	v_exp_f32_e32 v102, v107
	v_exp_f32_e32 v103, v123
	v_exp_f32_e32 v106, v108
	v_exp_f32_e32 v107, v124
	v_exp_f32_e32 v108, v109
	v_exp_f32_e32 v109, v125
	v_exp_f32_e32 v112, v110
	v_exp_f32_e32 v113, v126
	v_exp_f32_e32 v110, v111
	v_exp_f32_e32 v111, v127
	s_and_saveexec_b64 s[30:31], vcc
	s_xor_b64 s[30:31], exec, s[30:31]
	s_cbranch_execz .LBB0_91
	v_pk_add_f32 v[114:115], v[2:3], 0 op_sel_hi:[1,0]
	s_nop 0
	v_pk_add_f32 v[114:115], v[4:5], v[114:115]
	s_nop 0
	v_pk_add_f32 v[114:115], v[6:7], v[114:115]
	s_nop 0
	v_pk_add_f32 v[114:115], v[8:9], v[114:115]
	s_nop 0
	v_pk_add_f32 v[114:115], v[10:11], v[114:115]
	s_nop 0
	v_pk_add_f32 v[114:115], v[12:13], v[114:115]
	s_nop 0
	v_pk_add_f32 v[114:115], v[14:15], v[114:115]
	s_nop 0
	v_pk_add_f32 v[114:115], v[96:97], v[114:115]
	s_nop 0
	v_pk_add_f32 v[114:115], v[100:101], v[114:115]
	s_nop 0
	v_pk_add_f32 v[114:115], v[104:105], v[114:115]
	s_nop 0
	v_pk_add_f32 v[114:115], v[98:99], v[114:115]
	s_nop 0
	v_pk_add_f32 v[114:115], v[102:103], v[114:115]
	s_nop 0
	v_pk_add_f32 v[114:115], v[106:107], v[114:115]
	s_nop 0
	v_pk_add_f32 v[114:115], v[108:109], v[114:115]
	s_nop 0
	v_pk_add_f32 v[114:115], v[112:113], v[114:115]
	s_nop 0
	v_pk_add_f32 v[114:115], v[110:111], v[114:115]
	s_nop 0
	v_add_f32_e32 v114, v114, v115
	v_add_f32_e32 v186, v186, v114

; DI void diff_pass(const bf16_t* __restrict__ qrow  , const bf16_t* __restrict__ kg, const bf16_t* __restrict__ vg,
;                   int nkt, int q0, float negM2, f32x16 (&O)[4], float& lsum, char* lds) {
;     ...
;                 bf16x8 kf[2][4];
; #pragma unroll
;                 for (int kb = 0; kb < 2; ++kb)
; #pragma unroll
;                     for (int ks = 0; ks < 4; ++ks) kf[kb][ks] = *(const bf16x8*)(st + (32 * kb + l31) * 128 + (((2 * ks + h) ^ f) << 4));
;                 __builtin_amdgcn_sched_barrier(0);
; #pragma unroll
;                 for (int ks = 0; ks < 4; ++ks)
; #pragma unroll
;                     for (int kb = 0; kb < 2; ++kb) Sx[kb] = ks == 0 ? MFMA(kf[kb][0], qf[0], minit) : MFMA(kf[kb][ks], qf[ks], Sx[kb]);
;             }
;             if (kt * 64 + 63 > q0) {
; #pragma unroll
;                 for (int kb = 0; kb < 2; ++kb)
; #pragma unroll
;                     for (int i = 0; i < 16; ++i) {
;                         float p = fexp2(Sx[kb][i]);
;                         const int key = kt * 64 + 32 * kb + (i & 3) + 8 * (i >> 2) + 4 * h;
;                         if (key > qpos) p = 0.f;
;                         lsum += p; Sx[kb][i] = p;
;                     }
;             } else {
;                 float l0 = 0.f, l1 = 0.f;
; #pragma unroll
;                 for (int i = 0; i < 16; ++i) { const float p0 = fexp2(Sx[0][i]), p1 = fexp2(Sx[1][i]); l0 += p0; l1 += p1; Sx[0][i] = p0; Sx[1][i] = p1; }
;                 lsum += l0 + l1;
;             }
;             bf16x8 pf[4];
;             pf[0] = pack8(Sx[0], 0); pf[1] = pack8(Sx[0], 1); pf[2] = pack8(Sx[1], 0); pf[3] = pack8(Sx[1], 1);
;             {
;                 bf16x8 vf[2][4];
; #pragma unroll
;                 for (int db = 0; db < 4; ++db) vf[0][db] = *(const bf16x8*)(st + 8192 + (32 * db + l31) * 128 + ((h ^ f) << 4));
; #pragma unroll
;                 for (int s = 0; s < 4; ++s) {
;                     if (s < 3) {
; #pragma unroll
;                         for (int db = 0; db < 4; ++db) vf[(s + 1) & 1][db] = *(const bf16x8*)(st + 8192 + (32 * db + l31) * 128 + (((2 * (s + 1) + h) ^ f) << 4));
;                     }
; #pragma unroll
;                     for (int db = 0; db < 4; ++db) O[db] = MFMA(vf[s & 1][db], pf[s], O[db]);
;                     __builtin_amdgcn_sched_barrier(0);
;                 }
;             }
.Ldf_skipmid:
	s_or_b64 exec, exec, s[28:29]
	s_waitcnt vmcnt(2)
	s_barrier
	s_and_b32 s0, 1, s54
	s_cselect_b32 s0, 0, 0x6000
	v_add_u32_e32 v218, s0, v187
	v_lshl_add_u64 v[216:217], v[160:161], 0, v[158:159]
	s_mov_b64 s[0:1], 0x10000
	v_readfirstlane_b32 s32, v218
	v_lshl_add_u64 v[216:217], v[216:217], 0, s[0:1]
	s_mov_b32 m0, s32
	s_nop 0
	global_load_lds_dwordx4 v[216:217], off
	s_branch .LBB0_87
.Ldf_fast:
	ds_read_b128 v[2:5], v195
	ds_read_b128 v[10:13], v194
	ds_read_b128 v[200:203], v193
	ds_read_b128 v[208:211], v0
	ds_read_b128 v[6:9], v195 offset:4096
	ds_read_b128 v[196:199], v194 offset:4096
	ds_read_b128 v[204:207], v193 offset:4096
	ds_read_b128 v[212:215], v0 offset:4096
	v_mov_b32_e32 v14, 0
	v_mov_b32_e32 v15, 0
	s_waitcnt lgkmcnt(7)
	v_mfma_f32_32x32x16_bf16 v[96:111], v[2:5], v[140:143], v[16:31]
	s_waitcnt lgkmcnt(6)
	v_mfma_f32_32x32x16_bf16 v[96:111], v[10:13], v[136:139], v[96:111]
	s_waitcnt lgkmcnt(5)
	v_mfma_f32_32x32x16_bf16 v[96:111], v[200:203], v[132:135], v[96:111]
	s_waitcnt lgkmcnt(4)
	v_mfma_f32_32x32x16_bf16 v[96:111], v[208:211], v[128:131], v[96:111]
	s_waitcnt lgkmcnt(3)
	v_mfma_f32_32x32x16_bf16 v[112:127], v[6:9], v[140:143], v[16:31]
	s_waitcnt lgkmcnt(2)
	v_mfma_f32_32x32x16_bf16 v[112:127], v[196:199], v[136:139], v[112:127]
	s_nop 3
	v_exp_f32_e32 v96, v96
	v_exp_f32_e32 v97, v97
	v_add_f32_e32 v14, v14, v96
	v_add_f32_e32 v14, v14, v97
	s_waitcnt lgkmcnt(1)
	v_mfma_f32_32x32x16_bf16 v[112:127], v[204:207], v[132:135], v[112:127]
	v_exp_f32_e32 v98, v98
	v_exp_f32_e32 v99, v99
	v_add_f32_e32 v14, v14, v98
	v_add_f32_e32 v14, v14, v99
	s_waitcnt lgkmcnt(0)
	v_mfma_f32_32x32x16_bf16 v[112:127], v[212:215], v[128:131], v[112:127]
	s_waitcnt vmcnt(2)
	s_barrier
	s_and_b32 s0, 1, s54
	s_cselect_b32 s0, 0, 0x6000
	v_add_u32_e32 v218, s0, v187
	v_lshl_add_u64 v[216:217], v[160:161], 0, v[158:159]
	s_mov_b64 s[0:1], 0x10000
	v_readfirstlane_b32 s32, v218
	v_lshl_add_u64 v[216:217], v[216:217], 0, s[0:1]
	s_mov_b32 m0, s32
	s_nop 0
	global_load_lds_dwordx4 v[216:217], off
	ds_read_b128 v[2:5], v195 offset:8192
	ds_read_b128 v[10:13], v195 offset:12288
	ds_read_b128 v[200:203], v195 offset:16384
	ds_read_b128 v[208:211], v195 offset:20480
	v_exp_f32_e32 v100, v100
	v_exp_f32_e32 v101, v101
	v_add_f32_e32 v14, v14, v100
	v_add_f32_e32 v14, v14, v101
	v_exp_f32_e32 v102, v102
	v_exp_f32_e32 v103, v103
	v_add_f32_e32 v14, v14, v102
	v_add_f32_e32 v14, v14, v103
	v_cvt_pk_bf16_f32 v96, v96, v97
	v_cvt_pk_bf16_f32 v97, v98, v99
	v_cvt_pk_bf16_f32 v98, v100, v101
	v_cvt_pk_bf16_f32 v99, v102, v103
	s_waitcnt lgkmcnt(3)
	s_nop 0
	v_mfma_f32_32x32x16_bf16 v[80:95], v[2:5], v[96:99], v[80:95]
	ds_read_b128 v[6:9], v194 offset:8192
	ds_read_b128 v[196:199], v194 offset:12288
	ds_read_b128 v[204:207], v194 offset:16384
	ds_read_b128 v[212:215], v194 offset:20480
	v_exp_f32_e32 v104, v104
	v_exp_f32_e32 v105, v105
	v_add_f32_e32 v14, v14, v104
	v_add_f32_e32 v14, v14, v105
	s_waitcnt lgkmcnt(6)
	v_mfma_f32_32x32x16_bf16 v[64:79], v[10:13], v[96:99], v[64:79]
	ds_read_b128 v[2:5], v193 offset:8192
	v_exp_f32_e32 v106, v106
	v_exp_f32_e32 v107, v107
	v_add_f32_e32 v14, v14, v106
	v_add_f32_e32 v14, v14, v107
	s_waitcnt lgkmcnt(6)
	v_mfma_f32_32x32x16_bf16 v[48:63], v[200:203], v[96:99], v[48:63]
	ds_read_b128 v[10:13], v193 offset:12288
	v_exp_f32_e32 v108, v108
	v_exp_f32_e32 v109, v109
	v_add_f32_e32 v14, v14, v108
	v_add_f32_e32 v14, v14, v109
	s_waitcnt lgkmcnt(6)
	v_mfma_f32_32x32x16_bf16 v[32:47], v[208:211], v[96:99], v[32:47]
	ds_read_b128 v[200:203], v193 offset:16384
	v_exp_f32_e32 v110, v110
	v_exp_f32_e32 v111, v111
	v_add_f32_e32 v14, v14, v110
	v_add_f32_e32 v14, v14, v111
	v_cvt_pk_bf16_f32 v104, v104, v105
	v_cvt_pk_bf16_f32 v105, v106, v107
	v_cvt_pk_bf16_f32 v106, v108, v109
	v_cvt_pk_bf16_f32 v107, v110, v111
	s_waitcnt lgkmcnt(6)
	s_nop 0
	v_mfma_f32_32x32x16_bf16 v[80:95], v[6:9], v[104:107], v[80:95]
	ds_read_b128 v[208:211], v193 offset:20480
	v_exp_f32_e32 v112, v112
	v_exp_f32_e32 v113, v113
	v_add_f32_e32 v15, v15, v112
	v_add_f32_e32 v15, v15, v113
	s_waitcnt lgkmcnt(6)
	v_mfma_f32_32x32x16_bf16 v[64:79], v[196:199], v[104:107], v[64:79]
	ds_read_b128 v[6:9], v0 offset:8192
	v_exp_f32_e32 v114, v114
	v_exp_f32_e32 v115, v115
	v_add_f32_e32 v15, v15, v114
	v_add_f32_e32 v15, v15, v115
	s_waitcnt lgkmcnt(6)
	v_mfma_f32_32x32x16_bf16 v[48:63], v[204:207], v[104:107], v[48:63]
	ds_read_b128 v[196:199], v0 offset:12288
	v_exp_f32_e32 v116, v116
	v_exp_f32_e32 v117, v117
	v_add_f32_e32 v15, v15, v116
	v_add_f32_e32 v15, v15, v117
	s_waitcnt lgkmcnt(6)
	v_mfma_f32_32x32x16_bf16 v[32:47], v[212:215], v[104:107], v[32:47]
	ds_read_b128 v[204:207], v0 offset:16384
	v_exp_f32_e32 v118, v118
	v_exp_f32_e32 v119, v119
	v_add_f32_e32 v15, v15, v118
	v_add_f32_e32 v15, v15, v119
	v_cvt_pk_bf16_f32 v112, v112, v113
	v_cvt_pk_bf16_f32 v113, v114, v115
	v_cvt_pk_bf16_f32 v114, v116, v117
	v_cvt_pk_bf16_f32 v115, v118, v119
	s_waitcnt lgkmcnt(6)
	s_nop 0
	v_mfma_f32_32x32x16_bf16 v[80:95], v[2:5], v[112:115], v[80:95]
	ds_read_b128 v[212:215], v0 offset:20480
	v_exp_f32_e32 v120, v120
	v_exp_f32_e32 v121, v121
	v_add_f32_e32 v15, v15, v120
	v_add_f32_e32 v15, v15, v121
	s_waitcnt lgkmcnt(6)
	v_mfma_f32_32x32x16_bf16 v[64:79], v[10:13], v[112:115], v[64:79]
	v_exp_f32_e32 v122, v122
	v_exp_f32_e32 v123, v123
	v_add_f32_e32 v15, v15, v122
	v_add_f32_e32 v15, v15, v123
	s_waitcnt lgkmcnt(5)
	v_mfma_f32_32x32x16_bf16 v[48:63], v[200:203], v[112:115], v[48:63]
	v_exp_f32_e32 v124, v124
	v_exp_f32_e32 v125, v125
	v_add_f32_e32 v15, v15, v124
	v_add_f32_e32 v15, v15, v125
	s_waitcnt lgkmcnt(4)
	v_mfma_f32_32x32x16_bf16 v[32:47], v[208:211], v[112:115], v[32:47]
	v_exp_f32_e32 v126, v126
	v_exp_f32_e32 v127, v127
	v_add_f32_e32 v15, v15, v126
	v_add_f32_e32 v15, v15, v127
	v_cvt_pk_bf16_f32 v120, v120, v121
	v_cvt_pk_bf16_f32 v121, v122, v123
	v_cvt_pk_bf16_f32 v122, v124, v125
	v_cvt_pk_bf16_f32 v123, v126, v127
	v_add_f32_e32 v14, v14, v15
	s_waitcnt lgkmcnt(3)
	v_mfma_f32_32x32x16_bf16 v[80:95], v[6:9], v[120:123], v[80:95]
	v_add_f32_e32 v186, v186, v14
	s_waitcnt lgkmcnt(2)
	v_mfma_f32_32x32x16_bf16 v[64:79], v[196:199], v[120:123], v[64:79]
	s_waitcnt lgkmcnt(1)
	v_mfma_f32_32x32x16_bf16 v[48:63], v[204:207], v[120:123], v[48:63]
	s_waitcnt lgkmcnt(0)
	v_mfma_f32_32x32x16_bf16 v[32:47], v[212:215], v[120:123], v[32:47]
	s_branch .LBB0_87
